# v24 + grid-barrier spin loops poll with s_sleep 0 instead of s_sleep 1
# speedup vs baseline: 1.0000x; 1.0000x over previous
.LBB0_69:
	s_sleep 0
	global_load_dword v2, v0, s[0:1] offset:32 sc1
	s_waitcnt vmcnt(0)
	v_and_b32_e32 v2, 0xffff0000, v2
	v_cmp_ne_u32_e32 vcc, v2, v1
	s_or_b64 s[6:7], vcc, s[6:7]
	s_andn2_b64 exec, exec, s[6:7]
	s_cbranch_execnz .LBB0_69

; __device__ __forceinline__ unsigned xb_ld(unsigned* p)              { return __hip_atomic_load(p, __ATOMIC_RELAXED, __HIP_MEMORY_SCOPE_AGENT); }
; __device__ __forceinline__ void xcd_barrier_complete(unsigned* bar, unsigned x, unsigned& nloc, unsigned& nx) {
;     ...
;     for (;;) {
;         sum = 0u; cnt = 0u; mine = 0u;
; #pragma unroll
;         for (unsigned j = 0; j < 16; ++j) { const unsigned c = xb_ld(&bar[XB_XCNT(j)]); sum += c; cnt += (c > 0u) ? 1u : 0u; mine = (j == x) ? c : mine; }
;         if (sum == G) break;
;         __builtin_amdgcn_s_sleep(1);
;         if ((++sp & 255u) == 0u) { if (xb_ld(&bar[XB_TMO])) break; if (sp > XB_SPIN_CAP) { atomicAdd(&bar[XB_TMO], 1u); break; } }
;     }
.LBB0_81:
	global_load_dword v15, v16, s[50:51] offset:1024 sc1
	s_waitcnt lgkmcnt(0)
	global_load_dword v0, v16, s[50:51] offset:1280 sc1
	global_load_dword v1, v16, s[50:51] offset:1536 sc1
	global_load_dword v2, v16, s[50:51] offset:1792 sc1
	global_load_dword v3, v16, s[50:51] offset:2048 sc1
	global_load_dword v4, v16, s[50:51] offset:2304 sc1
	global_load_dword v5, v16, s[50:51] offset:2560 sc1
	global_load_dword v6, v16, s[50:51] offset:2816 sc1
	global_load_dword v7, v16, s[50:51] offset:3072 sc1
	global_load_dword v8, v16, s[50:51] offset:3328 sc1
	global_load_dword v9, v16, s[50:51] offset:3584 sc1
	global_load_dword v10, v16, s[50:51] offset:3840 sc1
	global_load_dword v11, v16, s[6:7] sc1
	global_load_dword v12, v16, s[8:9] sc1
	global_load_dword v13, v16, s[10:11] sc1
	global_load_dword v14, v16, s[12:13] sc1
	s_mov_b64 s[14:15], -1
	s_mov_b64 s[16:17], -1
	s_waitcnt vmcnt(14)
	v_add_u32_e32 v17, v0, v15
	s_waitcnt vmcnt(13)
	v_add_u32_e32 v17, v17, v1
	s_waitcnt vmcnt(12)
	v_add_u32_e32 v17, v17, v2
	s_waitcnt vmcnt(11)
	v_add_u32_e32 v17, v17, v3
	s_waitcnt vmcnt(10)
	v_add_u32_e32 v17, v17, v4
	s_waitcnt vmcnt(9)
	v_add_u32_e32 v17, v17, v5
	s_waitcnt vmcnt(8)
	v_add_u32_e32 v17, v17, v6
	s_waitcnt vmcnt(7)
	v_add_u32_e32 v17, v17, v7
	s_waitcnt vmcnt(6)
	v_add_u32_e32 v17, v17, v8
	s_waitcnt vmcnt(5)
	v_add_u32_e32 v17, v17, v9
	s_waitcnt vmcnt(4)
	v_add_u32_e32 v17, v17, v10
	s_waitcnt vmcnt(3)
	v_add_u32_e32 v17, v17, v11
	s_waitcnt vmcnt(2)
	v_add_u32_e32 v17, v17, v12
	s_waitcnt vmcnt(1)
	v_add_u32_e32 v17, v17, v13
	s_waitcnt vmcnt(0)
	v_add_u32_e32 v17, v17, v14
	v_cmp_eq_u32_e32 vcc, s3, v17
	s_cbranch_vccnz .LBB0_80
	s_and_b32 s14, s20, 0xff
	s_cmp_eq_u32 s14, 0
	s_mov_b64 s[14:15], -1
	s_mov_b64 s[18:19], -1
	s_sleep 0
	s_cbranch_scc0 .LBB0_85
	global_load_dword v17, v16, s[50:51] offset:512 sc1
	s_waitcnt vmcnt(0)
	v_cmp_eq_u32_e32 vcc, 0, v17
	s_cbranch_vccnz .LBB0_87
	s_mov_b64 s[18:19], 0

.LBB0_99:
	s_and_b32 s20, s3, 0xff
	s_mov_b64 s[18:19], -1
	s_cmp_lg_u32 s20, 0
	s_mov_b64 s[22:23], -1
	s_sleep 0
	s_cbranch_scc1 .LBB0_102
	global_load_dword v2, v0, s[50:51] offset:512 sc1
	s_waitcnt vmcnt(0)
	v_cmp_eq_u32_e32 vcc, 0, v2
	s_cbranch_vccnz .LBB0_104
	s_mov_b64 s[22:23], 0
	s_mov_b64 s[20:21], -1

.LBB0_116:
	s_and_b32 s20, s3, 0xff
	s_cmp_lg_u32 s20, 0
	s_mov_b64 s[22:23], -1
	s_sleep 0
	s_cbranch_scc1 .LBB0_119
	global_load_dword v1, v0, s[12:13] sc1
	s_waitcnt vmcnt(0)
	v_cmp_eq_u32_e32 vcc, 0, v1
	s_cbranch_vccnz .LBB0_121
	s_mov_b64 s[22:23], 0
	s_mov_b64 s[20:21], -1

; __device__ __forceinline__ unsigned xb_ld(unsigned* p)              { return __hip_atomic_load(p, __ATOMIC_RELAXED, __HIP_MEMORY_SCOPE_AGENT); }
; __device__ __forceinline__ void xcd_barrier_complete(unsigned* bar, unsigned x, unsigned& nloc, unsigned& nx) {
;     ...
;     for (;;) {
;         sum = 0u; cnt = 0u; mine = 0u;
; #pragma unroll
;         for (unsigned j = 0; j < 16; ++j) { const unsigned c = xb_ld(&bar[XB_XCNT(j)]); sum += c; cnt += (c > 0u) ? 1u : 0u; mine = (j == x) ? c : mine; }
;         if (sum == G) break;
;         __builtin_amdgcn_s_sleep(1);
;         if ((++sp & 255u) == 0u) { if (xb_ld(&bar[XB_TMO])) break; if (sp > XB_SPIN_CAP) { atomicAdd(&bar[XB_TMO], 1u); break; } }
;     }
.LBB0_244:
	global_load_dword v15, v205, s[50:51] offset:1024 sc1
	s_waitcnt lgkmcnt(0)
	global_load_dword v0, v205, s[50:51] offset:1280 sc1
	global_load_dword v1, v205, s[50:51] offset:1536 sc1
	global_load_dword v2, v205, s[50:51] offset:1792 sc1
	global_load_dword v3, v205, s[50:51] offset:2048 sc1
	global_load_dword v4, v205, s[50:51] offset:2304 sc1
	global_load_dword v5, v205, s[50:51] offset:2560 sc1
	global_load_dword v6, v205, s[50:51] offset:2816 sc1
	global_load_dword v7, v205, s[50:51] offset:3072 sc1
	global_load_dword v8, v205, s[50:51] offset:3328 sc1
	global_load_dword v9, v205, s[50:51] offset:3584 sc1
	global_load_dword v10, v205, s[50:51] offset:3840 sc1
	global_load_dword v11, v205, s[60:61] sc1
	global_load_dword v12, v205, s[62:63] sc1
	global_load_dword v13, v205, s[64:65] sc1
	global_load_dword v14, v205, s[66:67] sc1
	s_mov_b64 s[8:9], -1
	s_mov_b64 s[10:11], -1
	s_waitcnt vmcnt(14)
	v_add_u32_e32 v16, v0, v15
	s_waitcnt vmcnt(13)
	v_add_u32_e32 v16, v16, v1
	s_waitcnt vmcnt(12)
	v_add_u32_e32 v16, v16, v2
	s_waitcnt vmcnt(11)
	v_add_u32_e32 v16, v16, v3
	s_waitcnt vmcnt(10)
	v_add_u32_e32 v16, v16, v4
	s_waitcnt vmcnt(9)
	v_add_u32_e32 v16, v16, v5
	s_waitcnt vmcnt(8)
	v_add_u32_e32 v16, v16, v6
	s_waitcnt vmcnt(7)
	v_add_u32_e32 v16, v16, v7
	s_waitcnt vmcnt(6)
	v_add_u32_e32 v16, v16, v8
	s_waitcnt vmcnt(5)
	v_add_u32_e32 v16, v16, v9
	s_waitcnt vmcnt(4)
	v_add_u32_e32 v16, v16, v10
	s_waitcnt vmcnt(3)
	v_add_u32_e32 v16, v16, v11
	s_waitcnt vmcnt(2)
	v_add_u32_e32 v16, v16, v12
	s_waitcnt vmcnt(1)
	v_add_u32_e32 v16, v16, v13
	s_waitcnt vmcnt(0)
	v_add_u32_e32 v16, v16, v14
	v_cmp_eq_u32_e32 vcc, s49, v16
	s_cbranch_vccnz .LBB0_243
	s_and_b32 s8, s21, 0xff
	s_cmp_eq_u32 s8, 0
	s_mov_b64 s[8:9], -1
	s_mov_b64 s[16:17], -1
	s_sleep 0
	s_cbranch_scc0 .LBB0_248
	global_load_dword v16, v205, s[58:59] sc1
	s_waitcnt vmcnt(0)
	v_cmp_eq_u32_e32 vcc, 0, v16
	s_cbranch_vccnz .LBB0_250
	s_mov_b64 s[16:17], 0

.LBB0_262:
	s_and_b32 s22, s21, 0xff
	s_mov_b64 s[40:41], -1
	s_cmp_lg_u32 s22, 0
	s_mov_b64 s[44:45], -1
	s_sleep 0
	s_cbranch_scc1 .LBB0_265
	global_load_dword v0, v205, s[58:59] sc1
	s_waitcnt vmcnt(0)
	v_cmp_eq_u32_e32 vcc, 0, v0
	s_cbranch_vccnz .LBB0_267
	s_mov_b64 s[44:45], 0
	s_mov_b64 s[42:43], -1

.LBB0_457:
	s_and_b32 s22, s21, 0xff
	s_mov_b64 s[42:43], -1
	s_cmp_lg_u32 s22, 0
	s_mov_b64 s[46:47], -1
	s_sleep 0
	s_cbranch_scc1 .LBB0_460
	global_load_dword v0, v205, s[58:59] sc1
	s_waitcnt vmcnt(0)
	v_cmp_eq_u32_e32 vcc, 0, v0
	s_cbranch_vccnz .LBB0_462
	s_mov_b64 s[46:47], 0
	s_mov_b64 s[44:45], -1

.LBB0_539:
	s_and_b32 s22, s21, 0xff
	s_mov_b64 s[44:45], -1
	s_cmp_lg_u32 s22, 0
	s_mov_b64 s[68:69], -1
	s_sleep 0
	s_cbranch_scc1 .LBB0_542
	global_load_dword v0, v205, s[58:59] sc1
	s_waitcnt vmcnt(0)
	v_cmp_eq_u32_e32 vcc, 0, v0
	s_cbranch_vccnz .LBB0_544
	s_mov_b64 s[68:69], 0
	s_mov_b64 s[46:47], -1

; __device__ __forceinline__ unsigned xb_ld(unsigned* p)              { return __hip_atomic_load(p, __ATOMIC_RELAXED, __HIP_MEMORY_SCOPE_AGENT); }
; __device__ __forceinline__ void xcd_barrier_complete(unsigned* bar, unsigned x, unsigned& nloc, unsigned& nx) {
;     ...
;     for (;;) {
;         sum = 0u; cnt = 0u; mine = 0u;
; #pragma unroll
;         for (unsigned j = 0; j < 16; ++j) { const unsigned c = xb_ld(&bar[XB_XCNT(j)]); sum += c; cnt += (c > 0u) ? 1u : 0u; mine = (j == x) ? c : mine; }
;         if (sum == G) break;
;         __builtin_amdgcn_s_sleep(1);
;         if ((++sp & 255u) == 0u) { if (xb_ld(&bar[XB_TMO])) break; if (sp > XB_SPIN_CAP) { atomicAdd(&bar[XB_TMO], 1u); break; } }
;     }
.LBB0_618:
	global_load_dword v15, v205, s[50:51] offset:1024 sc1
	s_waitcnt lgkmcnt(0)
	global_load_dword v0, v205, s[50:51] offset:1280 sc1
	global_load_dword v1, v205, s[50:51] offset:1536 sc1
	global_load_dword v2, v205, s[50:51] offset:1792 sc1
	global_load_dword v3, v205, s[50:51] offset:2048 sc1
	global_load_dword v4, v205, s[50:51] offset:2304 sc1
	global_load_dword v5, v205, s[50:51] offset:2560 sc1
	global_load_dword v6, v205, s[50:51] offset:2816 sc1
	global_load_dword v7, v205, s[50:51] offset:3072 sc1
	global_load_dword v8, v205, s[50:51] offset:3328 sc1
	global_load_dword v9, v205, s[50:51] offset:3584 sc1
	global_load_dword v10, v205, s[50:51] offset:3840 sc1
	global_load_dword v11, v205, s[60:61] sc1
	global_load_dword v12, v205, s[62:63] sc1
	global_load_dword v13, v205, s[64:65] sc1
	global_load_dword v14, v205, s[66:67] sc1
	s_mov_b64 s[8:9], -1
	s_mov_b64 s[10:11], -1
	s_waitcnt vmcnt(14)
	v_add_u32_e32 v16, v0, v15
	s_waitcnt vmcnt(13)
	v_add_u32_e32 v16, v16, v1
	s_waitcnt vmcnt(12)
	v_add_u32_e32 v16, v16, v2
	s_waitcnt vmcnt(11)
	v_add_u32_e32 v16, v16, v3
	s_waitcnt vmcnt(10)
	v_add_u32_e32 v16, v16, v4
	s_waitcnt vmcnt(9)
	v_add_u32_e32 v16, v16, v5
	s_waitcnt vmcnt(8)
	v_add_u32_e32 v16, v16, v6
	s_waitcnt vmcnt(7)
	v_add_u32_e32 v16, v16, v7
	s_waitcnt vmcnt(6)
	v_add_u32_e32 v16, v16, v8
	s_waitcnt vmcnt(5)
	v_add_u32_e32 v16, v16, v9
	s_waitcnt vmcnt(4)
	v_add_u32_e32 v16, v16, v10
	s_waitcnt vmcnt(3)
	v_add_u32_e32 v16, v16, v11
	s_waitcnt vmcnt(2)
	v_add_u32_e32 v16, v16, v12
	s_waitcnt vmcnt(1)
	v_add_u32_e32 v16, v16, v13
	s_waitcnt vmcnt(0)
	v_add_u32_e32 v16, v16, v14
	v_cmp_eq_u32_e32 vcc, s49, v16
	s_cbranch_vccnz .LBB0_617
	s_and_b32 s8, s20, 0xff
	s_cmp_eq_u32 s8, 0
	s_mov_b64 s[8:9], -1
	s_mov_b64 s[16:17], -1
	s_sleep 0
	s_cbranch_scc0 .LBB0_622
	global_load_dword v16, v205, s[58:59] sc1
	s_waitcnt vmcnt(0)
	v_cmp_eq_u32_e32 vcc, 0, v16
	s_cbranch_vccnz .LBB0_624
	s_mov_b64 s[16:17], 0

.LBB0_636:
	s_and_b32 s21, s20, 0xff
	s_mov_b64 s[44:45], -1
	s_cmp_lg_u32 s21, 0
	s_mov_b64 s[68:69], -1
	s_sleep 0
	s_cbranch_scc1 .LBB0_639
	global_load_dword v0, v205, s[58:59] sc1
	s_waitcnt vmcnt(0)
	v_cmp_eq_u32_e32 vcc, 0, v0
	s_cbranch_vccnz .LBB0_641
	s_mov_b64 s[68:69], 0
	s_mov_b64 s[46:47], -1

.LBB0_754:
	s_and_b32 s21, s20, 0xff
	s_mov_b64 s[42:43], -1
	s_cmp_lg_u32 s21, 0
	s_mov_b64 s[46:47], -1
	s_sleep 0
	s_cbranch_scc1 .LBB0_757
	global_load_dword v0, v205, s[58:59] sc1
	s_waitcnt vmcnt(0)
	v_cmp_eq_u32_e32 vcc, 0, v0
	s_cbranch_vccnz .LBB0_759
	s_mov_b64 s[46:47], 0
	s_mov_b64 s[44:45], -1

.LBB0_808:
	s_and_b32 s21, s20, 0xff
	s_mov_b64 s[40:41], -1
	s_cmp_lg_u32 s21, 0
	s_mov_b64 s[44:45], -1
	s_sleep 0
	s_cbranch_scc1 .LBB0_811
	global_load_dword v0, v205, s[58:59] sc1
	s_waitcnt vmcnt(0)
	v_cmp_eq_u32_e32 vcc, 0, v0
	s_cbranch_vccnz .LBB0_813
	s_mov_b64 s[44:45], 0
	s_mov_b64 s[42:43], -1

; __device__ __forceinline__ unsigned xb_ld(unsigned* p)              { return __hip_atomic_load(p, __ATOMIC_RELAXED, __HIP_MEMORY_SCOPE_AGENT); }
; __device__ __forceinline__ void xcd_barrier_complete(unsigned* bar, unsigned x, unsigned& nloc, unsigned& nx) {
;     ...
;     for (;;) {
;         sum = 0u; cnt = 0u; mine = 0u;
; #pragma unroll
;         for (unsigned j = 0; j < 16; ++j) { const unsigned c = xb_ld(&bar[XB_XCNT(j)]); sum += c; cnt += (c > 0u) ? 1u : 0u; mine = (j == x) ? c : mine; }
;         if (sum == G) break;
;         __builtin_amdgcn_s_sleep(1);
;         if ((++sp & 255u) == 0u) { if (xb_ld(&bar[XB_TMO])) break; if (sp > XB_SPIN_CAP) { atomicAdd(&bar[XB_TMO], 1u); break; } }
;     }
.LBB0_825:
	global_load_dword v15, v205, s[50:51] offset:1024 sc1
	s_waitcnt lgkmcnt(0)
	global_load_dword v0, v205, s[50:51] offset:1280 sc1
	global_load_dword v1, v205, s[50:51] offset:1536 sc1
	global_load_dword v2, v205, s[50:51] offset:1792 sc1
	global_load_dword v3, v205, s[50:51] offset:2048 sc1
	global_load_dword v4, v205, s[50:51] offset:2304 sc1
	global_load_dword v5, v205, s[50:51] offset:2560 sc1
	global_load_dword v6, v205, s[50:51] offset:2816 sc1
	global_load_dword v7, v205, s[50:51] offset:3072 sc1
	global_load_dword v8, v205, s[50:51] offset:3328 sc1
	global_load_dword v9, v205, s[50:51] offset:3584 sc1
	global_load_dword v10, v205, s[50:51] offset:3840 sc1
	global_load_dword v11, v205, s[60:61] sc1
	global_load_dword v12, v205, s[62:63] sc1
	global_load_dword v13, v205, s[64:65] sc1
	global_load_dword v14, v205, s[66:67] sc1
	s_mov_b64 s[6:7], -1
	s_mov_b64 s[8:9], -1
	s_waitcnt vmcnt(14)
	v_add_u32_e32 v16, v0, v15
	s_waitcnt vmcnt(13)
	v_add_u32_e32 v16, v16, v1
	s_waitcnt vmcnt(12)
	v_add_u32_e32 v16, v16, v2
	s_waitcnt vmcnt(11)
	v_add_u32_e32 v16, v16, v3
	s_waitcnt vmcnt(10)
	v_add_u32_e32 v16, v16, v4
	s_waitcnt vmcnt(9)
	v_add_u32_e32 v16, v16, v5
	s_waitcnt vmcnt(8)
	v_add_u32_e32 v16, v16, v6
	s_waitcnt vmcnt(7)
	v_add_u32_e32 v16, v16, v7
	s_waitcnt vmcnt(6)
	v_add_u32_e32 v16, v16, v8
	s_waitcnt vmcnt(5)
	v_add_u32_e32 v16, v16, v9
	s_waitcnt vmcnt(4)
	v_add_u32_e32 v16, v16, v10
	s_waitcnt vmcnt(3)
	v_add_u32_e32 v16, v16, v11
	s_waitcnt vmcnt(2)
	v_add_u32_e32 v16, v16, v12
	s_waitcnt vmcnt(1)
	v_add_u32_e32 v16, v16, v13
	s_waitcnt vmcnt(0)
	v_add_u32_e32 v16, v16, v14
	v_cmp_eq_u32_e32 vcc, s49, v16
	s_cbranch_vccnz .LBB0_824
	s_and_b32 s6, s16, 0xff
	s_cmp_eq_u32 s6, 0
	s_mov_b64 s[6:7], -1
	s_mov_b64 s[10:11], -1
	s_sleep 0
	s_cbranch_scc0 .LBB0_829
	global_load_dword v16, v205, s[58:59] sc1
	s_waitcnt vmcnt(0)
	v_cmp_eq_u32_e32 vcc, 0, v16
	s_cbranch_vccnz .LBB0_831
	s_mov_b64 s[10:11], 0

.LBB0_843:
	s_and_b32 s21, s20, 0xff
	s_mov_b64 s[38:39], -1
	s_cmp_lg_u32 s21, 0
	s_mov_b64 s[42:43], -1
	s_sleep 0
	s_cbranch_scc1 .LBB0_846
	global_load_dword v0, v205, s[58:59] sc1
	s_waitcnt vmcnt(0)
	v_cmp_eq_u32_e32 vcc, 0, v0
	s_cbranch_vccnz .LBB0_848
	s_mov_b64 s[42:43], 0
	s_mov_b64 s[40:41], -1
